# P7 EpiD exchange: returning arrival atomic, last arriver skips the poll round trip
# speedup vs baseline: 1.0024x; 1.0024x over previous
;     __device__ __forceinline__ void fused(f32x4 (&acc)[2][2][4][2], const pg8::Unit& u, int wr, int wc, int fr, int fq, LAS unsigned char* lds, int wid, int lane) const {
;     ...
;         asm volatile("s_waitcnt vmcnt(0)" ::: "memory");
;         __syncthreads();
;         if (tid == 0) {
;             unsigned* c = cnt + 64 * u.pm;
;             (void)__hip_atomic_fetch_add(c, 1u, __ATOMIC_RELAXED, __HIP_MEMORY_SCOPE_AGENT);
;             unsigned sp = 0;
;             while (__hip_atomic_load(c, __ATOMIC_RELAXED, __HIP_MEMORY_SCOPE_AGENT) < 4u) { __builtin_amdgcn_s_sleep(2); if (++sp > (1u << 22)) break; }
;             __builtin_amdgcn_fence(__ATOMIC_ACQUIRE, "agent");
;             asm volatile("s_waitcnt vmcnt(0)" ::: "memory");
.LBB0_793:
	s_or_b64 exec, exec, s[6:7]
	s_waitcnt vmcnt(0)
	s_barrier
	s_and_saveexec_b64 s[6:7], s[92:93]
	s_cbranch_execz .LBB0_805
	s_lshl_b32 s0, s8, 6
	s_ashr_i32 s1, s0, 31
	s_lshl_b64 s[0:1], s[0:1], 2
	s_mov_b64 s[10:11], exec
	s_add_u32 s0, s66, s0
	s_addc_u32 s1, s67, s1
	v_mbcnt_lo_u32_b32 v0, s10, 0
	s_add_u32 s0, s0, 0x4000
	v_mbcnt_hi_u32_b32 v0, s11, v0
	s_addc_u32 s1, s1, 0
	v_cmp_eq_u32_e32 vcc, 0, v0
	s_and_saveexec_b64 s[12:13], vcc
	s_cbranch_execz .LBB0_796
	s_bcnt1_i32_b64 s10, s[10:11]
	v_mov_b32_e32 v0, 0
	v_mov_b32_e32 v1, s10
	global_atomic_add v1, v0, v1, s[0:1] sc0
.LBB0_796:
	s_or_b64 exec, exec, s[12:13]
	s_waitcnt vmcnt(0)
	v_readfirstlane_b32 s12, v1
	s_cmp_ge_u32 s12, 3
	s_cbranch_scc1 .LBB0_804
	s_mov_b32 s12, 0x400001
	v_mov_b32_e32 v0, 0
	s_branch .LBB0_798
